# phase 0: rope table split across all 256 workgroups (1/8 slice of an item pair each) and adaLN prep_mod pairs not needed before phase 6 moved to idle workgroups of phase 5's short last round
# speedup vs baseline: 1.0040x; 1.0027x over previous
.LBB0_18:
	s_add_u32 s2, s50, 0xc8
	s_addc_u32 s3, s51, 0
	v_writelane_b32 v254, s2, 2
	s_lshr_b32 s65, s10, 8
	s_bfe_u32 s49, s10, 0x20006
	v_writelane_b32 v254, s3, 3
	s_mul_i32 s2, s65, 0x13c00
	s_add_i32 s33, s2, 0
	s_lshl_b32 s2, s49, 5
	v_writelane_b32 v254, s2, 4
	s_add_i32 s2, s33, 0x12000
	v_writelane_b32 v254, s2, 5
	s_add_i32 s2, s33, 0x13400
	s_and_b32 s48, s10, 0xffffffc0
	s_add_i32 s73, s33, 0x11c00
	s_add_i32 s60, s33, 0x12400
	s_add_i32 s64, s33, 0x12800
	s_add_i32 s72, s33, 0x12c00
	v_writelane_b32 v254, s2, 6
	s_add_i32 s2, s33, 0x13410
	s_cmp_eq_u32 s49, 0
	s_cselect_b64 s[52:53], -1, 0
	s_cmp_lg_u32 s49, 0
	v_writelane_b32 v254, s2, 7
	s_cselect_b64 s[2:3], -1, 0
	s_cmp_gt_u32 s49, 1
	v_writelane_b32 v254, s2, 8
	s_cselect_b64 s[92:93], -1, 0
	s_cmp_lg_u32 s49, 1
	v_writelane_b32 v254, s3, 9
	s_cselect_b64 s[2:3], -1, 0
	s_cmp_eq_u32 s49, 3
	s_cselect_b64 s[76:77], -1, 0
	s_cmp_lg_u32 s49, 3
	s_cselect_b64 s[62:63], -1, 0
	s_cmp_lt_u32 s49, 2
	v_writelane_b32 v254, s2, 10
	s_cselect_b64 s[80:81], -1, 0
	s_cmp_lg_u32 s49, 2
	v_writelane_b32 v254, s3, 11
	s_cselect_b64 s[2:3], -1, 0
	v_writelane_b32 v254, s2, 12
	v_lshrrev_b32_e32 v2, 20, v0
	v_lshrrev_b32_e32 v0, 10, v0
	v_writelane_b32 v254, s3, 13
	s_add_i32 s2, s65, 0x3f8
	v_writelane_b32 v254, s2, 14
	s_add_i32 s2, s65, 0x238
	v_writelane_b32 v254, s2, 15
	s_add_i32 s2, s65, 0xffffff3c
	v_writelane_b32 v254, s2, 16
	s_add_i32 s2, s65, 0x78
	v_writelane_b32 v254, s2, 17
	s_lshl_b32 s2, s65, 12
	s_add_u32 s3, s0, 0xdac8600
	v_writelane_b32 v254, s3, 18
	s_addc_u32 s3, s1, 0
	s_add_u32 s4, s0, 0xdac8800
	v_writelane_b32 v254, s3, 19
	s_addc_u32 s5, s1, 0
	v_writelane_b32 v254, s4, 20
	v_or_b32_e32 v0, v0, v2
	s_mov_b32 s24, s26
	v_writelane_b32 v254, s5, 21
	s_add_u32 s4, s0, 0xdac8a00
	s_addc_u32 s5, s1, 0
	v_writelane_b32 v254, s4, 22
	v_mov_b32_e32 v161, 0
	v_mov_b32_e32 v252, 0x358637bd
	v_writelane_b32 v254, s5, 23
	s_add_u32 s4, s0, 0xdac8b00
	s_addc_u32 s5, s1, 0
	v_writelane_b32 v254, s4, 24
	v_mov_b32_e32 v163, 0x33ac000
	v_mov_b32_e32 v230, 0x33b4000
	v_writelane_b32 v254, s5, 25
	s_add_u32 s4, s0, 0xdac8c00
	s_addc_u32 s5, s1, 0
	v_writelane_b32 v254, s4, 26
	v_mov_b32_e32 v231, 0x3c0881c4
	v_mov_b32_e32 v247, 0xbab64f3b
	v_writelane_b32 v254, s5, 27
	s_add_u32 s4, s0, 0xdac8d00
	s_addc_u32 s5, s1, 0
	v_writelane_b32 v254, s4, 28
	v_mov_b32_e32 v162, 0x7f800000
	v_not_b32_e32 v250, 63
	v_writelane_b32 v254, s5, 29
	s_add_u32 s4, s0, 0xdac8e00
	s_addc_u32 s5, s1, 0
	v_writelane_b32 v254, s4, 30
	v_not_b32_e32 v246, 31
	v_mov_b32_e32 v251, 0x7fc00000
	v_writelane_b32 v254, s5, 31
	s_add_u32 s4, s0, 0xdac8f00
	s_addc_u32 s5, s1, 0
	v_writelane_b32 v254, s4, 32
	s_movk_i32 s39, 0x4000
	s_movk_i32 s42, 0xc00
	v_writelane_b32 v254, s5, 33
	s_add_u32 s4, s0, 0xdac9000
	s_addc_u32 s5, s1, 0
	v_writelane_b32 v254, s4, 34
	s_mov_b32 s84, 0x800000
	s_movk_i32 s85, 0x60
	v_writelane_b32 v254, s5, 35
	s_add_u32 s4, s0, 0xdac9100
	s_addc_u32 s5, s1, 0
	v_writelane_b32 v254, s4, 36
	s_mov_b32 s56, 0x3fb8aa3b
	s_movk_i32 s90, 0x42
	v_writelane_b32 v254, s5, 37
	s_add_u32 s4, s0, 0xdac9200
	s_addc_u32 s5, s1, 0
	v_writelane_b32 v254, s4, 38
	s_mov_b32 s91, 0x3f317217
	s_movk_i32 s68, 0x1020
	v_writelane_b32 v254, s5, 39
	s_add_u32 s4, s0, 0xdac9300
	s_addc_u32 s5, s1, 0
	v_writelane_b32 v254, s4, 40
	s_movk_i32 s61, 0x204
	s_mov_b32 s69, 0
	v_writelane_b32 v254, s5, 41
	s_add_u32 s4, s0, 0xdac9400
	s_addc_u32 s5, s1, 0
	v_writelane_b32 v254, s4, 42
	s_mov_b64 s[70:71], 0x7668680
	s_mov_b64 s[74:75], 0x75b8700
	v_writelane_b32 v254, s5, 43
	s_add_u32 s4, s0, 0xdac9500
	s_addc_u32 s5, s1, 0
	v_writelane_b32 v254, s4, 44
	s_mov_b64 s[78:79], 0x7668700
	s_mov_b64 s[82:83], 0x75b8780
	v_writelane_b32 v254, s5, 45
	s_add_u32 s4, s0, 0xdac9600
	s_addc_u32 s5, s1, 0
	v_writelane_b32 v254, s4, 46
	s_mov_b64 s[86:87], 0x100
	s_mov_b64 s[88:89], 0x40080
	v_writelane_b32 v254, s5, 47
	s_add_u32 s4, s0, 0xdac9700
	s_addc_u32 s5, s1, 0
	v_writelane_b32 v254, s4, 48
	s_mov_b64 s[94:95], 0x40100
	s_mov_b64 s[40:41], 0x180
	v_writelane_b32 v254, s5, 49
	s_add_u32 s4, s0, 0xdac9800
	s_addc_u32 s5, s1, 0
	v_writelane_b32 v254, s4, 50
	s_nop 1
	v_writelane_b32 v254, s5, 51
	s_add_u32 s4, s0, 0xdac9900
	s_addc_u32 s5, s1, 0
	v_writelane_b32 v254, s4, 52
	s_nop 1
	v_writelane_b32 v254, s5, 53
	s_add_u32 s4, s0, 0xdacba00
	s_addc_u32 s5, s1, 0
	v_writelane_b32 v254, s4, 54
	s_add_u32 s0, s0, 0xdacbb00
	s_addc_u32 s1, s1, 0
	v_writelane_b32 v254, s5, 55
	v_writelane_b32 v254, s0, 56
	s_nop 1
	v_writelane_b32 v254, s1, 57
	s_movk_i32 s0, 0x3ff
	v_and_or_b32 v0, v0, s0, v1
	s_add_i32 s0, s2, 0xffe7e000
	v_writelane_b32 v254, s0, 58
	s_lshl_b32 s0, s65, 13
	s_add_i32 s0, s0, 0xffcfc000
	v_writelane_b32 v254, s0, 59
	s_add_i32 s0, s33, 0x4800
	v_writelane_b32 v254, s0, 60
	s_add_i32 s0, 0, 0x10000
	v_writelane_b32 v254, s0, 61
	s_add_i32 s0, 0, 0x14000
	v_writelane_b32 v254, s0, 62
	s_add_i32 s0, 0, 0x18000
	v_writelane_b32 v254, s0, 63
	s_add_i32 s0, 0, 0x1c000
	v_writelane_b32 v255, s0, 0
	v_cmp_eq_u32_e64 s[0:1], 0, v0
	s_nop 1
	v_writelane_b32 v255, s0, 1
	s_nop 1
	v_writelane_b32 v255, s1, 2
	v_writelane_b32 v255, s50, 3
	s_nop 1
	v_writelane_b32 v255, s51, 4
	v_writelane_b32 v255, s26, 5
	s_nop 1
	v_writelane_b32 v255, s27, 6
	s_mov_b32 s0, 0
	v_writelane_b32 v255, s0, 21
	v_writelane_b32 v255, s0, 16
	s_branch .LBB0_23

.LBB0_1138:
	s_not_b32 s0, s34
	s_add_i32 s0, s31, s0
	s_cmpk_gt_i32 s0, 0x1f
	s_mov_b32 s1, s0
	s_cbranch_scc0 .LBB0_1142
.LBB0_1139:
	v_readlane_b32 s2, v255, 16
	s_cmp_lg_u32 s2, 0
	s_cbranch_scc1 .Lmd_ret
	v_readlane_b32 s0, v255, 8
	s_and_b32 s32, s0, 7
	s_lshl_b32 s32, s32, 10
	s_add_i32 s42, s32, 0x400
	s_lshr_b32 s0, s0, 3
	s_sub_i32 s2, 63, s0
	v_writelane_b32 v255, s2, 8
	s_add_u32 s12, s46, 0x30a4000
	v_readlane_b32 s31, v255, 9
	s_addc_u32 s13, s47, 0
	s_lshl_b32 s1, s31, 13
	v_readlane_b32 s2, v254, 58
	v_readlane_b32 s5, v255, 8
	s_add_i32 s2, s2, s1
	s_lshl_b32 s3, s5, 13
	s_sub_i32 s2, s2, s3
	s_lshl_b32 s3, s31, 14
	v_readlane_b32 s4, v254, 59
	s_add_i32 s4, s4, s3
	s_lshl_b32 s5, s5, 14
	s_sub_i32 s16, s4, s5
	s_mov_b32 s19, 0x7f800000
	s_mov_b32 s20, 0xc2ce8ed0
	s_mov_b32 s21, 0x42b17218
	s_mov_b32 s22, 0xfe5163ab
	s_mov_b32 s23, 0x3c439041
	s_mov_b32 s24, 0xdb629599
	s_mov_b32 s25, 0xf534ddc0
	s_mov_b32 s26, 0xfc2757d1
	s_mov_b32 s27, 0x4e441529
	s_mov_b32 s28, 0xa2f9836e
	s_mov_b32 s29, 0x3fc90fda
	s_mov_b32 s30, 0xbfc90fda
	s_waitcnt vmcnt(0)
	s_branch .LBB0_1149

.LBB0_1149:
	s_mov_b32 s17, s32
	s_lshr_b32 s18, s32, 1
	s_add_i32 s18, s18, s2
	s_branch .LBB0_1151
.LBB0_1150:
	s_or_b64 exec, exec, s[4:5]
	v_mul_f32_e32 v4, v8, v8
	v_fmamk_f32 v5, v4, 0xb94c1982, v231
	v_fmaak_f32 v5, v4, v5, 0xbe2aaa9d
	v_mul_f32_e32 v5, v4, v5
	v_fmac_f32_e32 v8, v8, v5
	v_fmamk_f32 v5, v4, 0x37d75334, v247
	v_fmaak_f32 v5, v4, v5, 0x3d2aabf7
	v_fmaak_f32 v5, v4, v5, 0xbf000004
	v_fma_f32 v4, v4, v5, 1.0
	v_and_b32_e32 v5, 1, v7
	v_cmp_eq_u32_e64 s[4:5], 0, v5
	v_lshlrev_b32_e32 v5, 30, v7
	v_and_b32_e32 v5, 0x80000000, v5
	v_xor_b32_e32 v2, v3, v2
	v_cndmask_b32_e64 v4, v4, v8, s[4:5]
	v_xor_b32_e32 v2, v2, v5
	v_xor_b32_e32 v2, v2, v4
	s_addk_i32 s17, 0x200
	s_addk_i32 s18, 0x100
	v_cndmask_b32_e32 v2, v251, v2, vcc
	s_cmp_lg_u32 s17, s42
	global_store_dword v[0:1], v2, off offset:128
	s_cbranch_scc0 .LBB0_1148

.Lrs_ret:
	v_writelane_b32 v255, s43, 8
.LBB0_1159:
	s_cmp_eq_u32 s66, 5
	s_cbranch_scc0 .Lmd_skip
	v_readlane_b32 s0, v255, 8
	s_cmp_lt_u32 s0, 0x60
	s_cbranch_scc1 .Lmd_skip
	s_add_i32 s1, s0, 0xffffffc0
	v_readlane_b32 s31, v255, 9
	s_cmp_lg_u32 s31, 0x100
	s_cbranch_scc1 .Lmd_skip
	v_readlane_b32 s54, v255, 3
	v_readlane_b32 s55, v255, 4
	s_load_dwordx2 s[16:17], s[54:55], 0xb8
	s_mov_b32 s30, 0xbfb8aa3b
	s_movk_i32 s85, 0x60
	s_mov_b32 s2, 1
	s_waitcnt vmcnt(0) lgkmcnt(0)
	s_add_u32 s16, s16, 0x3080000
	s_addc_u32 s17, s17, 0
	s_mov_b64 exec, -1
	v_mov_b32_e32 v162, 0x7f800000
	v_writelane_b32 v255, s2, 16
	s_barrier
	s_branch .LBB0_1142
.Lmd_ret:
	s_mov_b32 s2, 0
	v_writelane_b32 v255, s2, 16
